# 64B-align the nine GEMM K-loop heads on top of pipelined GQA
# speedup vs baseline: 1.0041x; 1.0022x over previous
;     __device__ __forceinline__ const char* ptrA(const Unit& u) const { return (u.sub ? A1 : A0) + (size_t)u.pm * aT; }
;     __device__ __forceinline__ const char* ptrB(const Unit& u) const { return (u.sub ? B1 : B0) + (size_t)u.pn * bT; }
;     __device__ __forceinline__ bool next(int i, Unit& u) const { const int L = i * G + c; if (L >= 256) return false; u.sub = L & 3; const int t = L >> 2; u.pm = 64 + (t >> 3); u.pn = t & 7; return true; }
; template <bool F8 = false, class Epi, class Sched>
; __device__ __forceinline__ void gemm_phase(LAS unsigned char* lds, const int lda, const int ldb, const int K, const Sched& S, const Epi& E) {
;     ...
;         const bool has_next = S.next(ui + 1, nxt);
;         const char* nA = has_next ? S.ptrA(nxt) : cA; const char* nB = has_next ? S.ptrB(nxt) : cB;
;     ...
; #pragma unroll
;         for (int a = 0; a < 2; ++a)
; #pragma unroll
;             for (int b = 0; b < 2; ++b)
; #pragma unroll
;                 for (int m = 0; m < 4; ++m)
; #pragma unroll
;                     for (int n = 0; n < 2; ++n) acc[a][b][m][n] = (f32x4){0.f, 0.f, 0.f, 0.f};
;         cur = nxt; cA = nA; cB = nB; ++ui;
.LBB0_241:
	s_ashr_i32 s13, s12, 31
	s_lshl_b64 s[18:19], s[12:13], 20
	s_add_u32 s18, s82, s18
	s_addc_u32 s19, s83, s19
	s_and_b64 s[20:21], s[16:17], exec
	s_cselect_b32 s5, s19, s53
	s_cselect_b32 s13, s18, s52
	s_ashr_i32 s11, s10, 31
	s_lshl_b64 s[20:21], s[10:11], 20
	v_readlane_b32 s11, v251, 22
	s_add_u32 s20, s11, s20
	v_readlane_b32 s11, v251, 23
	s_addc_u32 s21, s11, s21
	s_and_b64 s[28:29], s[16:17], exec
	s_cselect_b32 s11, s21, s75
	s_cselect_b32 s15, s20, s74
	s_add_u32 s72, s52, 0x80080
	s_addc_u32 s73, s53, 0
	s_add_u32 vcc_lo, s74, 0x100
	v_mov_b32_e32 v2, 0
	s_addc_u32 vcc_hi, s75, 0
	s_mov_b32 s28, -2
	v_mov_b32_e32 v3, v2
	v_mov_b32_e32 v4, v2
	v_mov_b32_e32 v5, v2
	v_mov_b32_e32 v6, v2
	v_mov_b32_e32 v7, v2
	v_mov_b32_e32 v8, v2
	v_mov_b32_e32 v9, v2
	v_mov_b32_e32 v14, v2
	v_mov_b32_e32 v15, v2
	v_mov_b32_e32 v16, v2
	v_mov_b32_e32 v17, v2
	v_mov_b32_e32 v22, v2
	v_mov_b32_e32 v23, v2
	v_mov_b32_e32 v24, v2
	v_mov_b32_e32 v25, v2
	v_mov_b32_e32 v30, v2
	v_mov_b32_e32 v31, v2
	v_mov_b32_e32 v32, v2
	v_mov_b32_e32 v33, v2
	v_mov_b32_e32 v38, v2
	v_mov_b32_e32 v39, v2
	v_mov_b32_e32 v40, v2
	v_mov_b32_e32 v41, v2
	v_mov_b32_e32 v46, v2
	v_mov_b32_e32 v47, v2
	v_mov_b32_e32 v48, v2
	v_mov_b32_e32 v49, v2
	v_mov_b32_e32 v54, v2
	v_mov_b32_e32 v55, v2
	v_mov_b32_e32 v56, v2
	v_mov_b32_e32 v57, v2
	v_mov_b32_e32 v10, v2
	v_mov_b32_e32 v11, v2
	v_mov_b32_e32 v12, v2
	v_mov_b32_e32 v13, v2
	v_mov_b32_e32 v18, v2
	v_mov_b32_e32 v19, v2
	v_mov_b32_e32 v20, v2
	v_mov_b32_e32 v21, v2
	v_mov_b32_e32 v26, v2
	v_mov_b32_e32 v27, v2
	v_mov_b32_e32 v28, v2
	v_mov_b32_e32 v29, v2
	v_mov_b32_e32 v34, v2
	v_mov_b32_e32 v35, v2
	v_mov_b32_e32 v36, v2
	v_mov_b32_e32 v37, v2
	v_mov_b32_e32 v42, v2
	v_mov_b32_e32 v43, v2
	v_mov_b32_e32 v44, v2
	v_mov_b32_e32 v45, v2
	v_mov_b32_e32 v50, v2
	v_mov_b32_e32 v51, v2
	v_mov_b32_e32 v52, v2
	v_mov_b32_e32 v53, v2
	v_mov_b32_e32 v58, v2
	v_mov_b32_e32 v59, v2
	v_mov_b32_e32 v60, v2
	v_mov_b32_e32 v61, v2
	v_mov_b32_e32 v62, v2
	v_mov_b32_e32 v63, v2
	v_mov_b32_e32 v64, v2
	v_mov_b32_e32 v65, v2
	v_mov_b32_e32 v66, v2
	v_mov_b32_e32 v67, v2
	v_mov_b32_e32 v68, v2
	v_mov_b32_e32 v69, v2
	v_mov_b32_e32 v70, v2
	v_mov_b32_e32 v71, v2
	v_mov_b32_e32 v72, v2
	v_mov_b32_e32 v73, v2
	v_mov_b32_e32 v78, v2
	v_mov_b32_e32 v79, v2
	v_mov_b32_e32 v80, v2
	v_mov_b32_e32 v81, v2
	v_mov_b32_e32 v86, v2
	v_mov_b32_e32 v87, v2
	v_mov_b32_e32 v88, v2
	v_mov_b32_e32 v89, v2
	v_mov_b32_e32 v94, v2
	v_mov_b32_e32 v95, v2
	v_mov_b32_e32 v96, v2
	v_mov_b32_e32 v97, v2
	v_mov_b32_e32 v102, v2
	v_mov_b32_e32 v103, v2
	v_mov_b32_e32 v104, v2
	v_mov_b32_e32 v105, v2
	v_mov_b32_e32 v110, v2
	v_mov_b32_e32 v111, v2
	v_mov_b32_e32 v112, v2
	v_mov_b32_e32 v113, v2
	v_mov_b32_e32 v118, v2
	v_mov_b32_e32 v119, v2
	v_mov_b32_e32 v120, v2
	v_mov_b32_e32 v121, v2
	v_mov_b32_e32 v74, v2
	v_mov_b32_e32 v75, v2
	v_mov_b32_e32 v76, v2
	v_mov_b32_e32 v77, v2
	v_mov_b32_e32 v82, v2
	v_mov_b32_e32 v83, v2
	v_mov_b32_e32 v84, v2
	v_mov_b32_e32 v85, v2
	v_mov_b32_e32 v90, v2
	v_mov_b32_e32 v91, v2
	v_mov_b32_e32 v92, v2
	v_mov_b32_e32 v93, v2
	v_mov_b32_e32 v98, v2
	v_mov_b32_e32 v99, v2
	v_mov_b32_e32 v100, v2
	v_mov_b32_e32 v101, v2
	v_mov_b32_e32 v106, v2
	v_mov_b32_e32 v107, v2
	v_mov_b32_e32 v108, v2
	v_mov_b32_e32 v109, v2
	v_mov_b32_e32 v114, v2
	v_mov_b32_e32 v115, v2
	v_mov_b32_e32 v116, v2
	v_mov_b32_e32 v117, v2
	v_mov_b32_e32 v122, v2
	v_mov_b32_e32 v123, v2
	v_mov_b32_e32 v124, v2
	v_mov_b32_e32 v125, v2
	v_mov_b32_e32 v126, v2
	v_mov_b32_e32 v127, v2
	v_mov_b32_e32 v128, v2
	v_mov_b32_e32 v129, v2
	.p2align	6

;     __device__ __forceinline__ const char* ptrA(const Unit& u) const { return (u.sub ? A1 : A0) + (size_t)u.pm * aT; }
;     __device__ __forceinline__ const char* ptrB(const Unit& u) const { return (u.sub ? B1 : B0) + (size_t)u.pn * bT; }
;     __device__ __forceinline__ bool next(int i, Unit& u) const { const int L = i * G + c; if (L >= 256) return false; u.sub = L & 3; const int t = L >> 2; u.pm = 64 + (t >> 3); u.pn = t & 7; return true; }
; template <bool F8 = false, class Epi, class Sched>
; __device__ __forceinline__ void gemm_phase(LAS unsigned char* lds, const int lda, const int ldb, const int K, const Sched& S, const Epi& E) {
;     ...
;         const bool has_next = S.next(ui + 1, nxt);
;         const char* nA = has_next ? S.ptrA(nxt) : cA; const char* nB = has_next ? S.ptrB(nxt) : cB;
;     ...
; #pragma unroll
;         for (int a = 0; a < 2; ++a)
; #pragma unroll
;             for (int b = 0; b < 2; ++b)
; #pragma unroll
;                 for (int m = 0; m < 4; ++m)
; #pragma unroll
;                     for (int n = 0; n < 2; ++n) acc[a][b][m][n] = (f32x4){0.f, 0.f, 0.f, 0.f};
;         cur = nxt; cA = nA; cB = nB; ++ui;
.LBB0_291:
	s_ashr_i32 s11, s10, 31
	s_lshl_b64 s[20:21], s[10:11], 19
	s_add_u32 s20, s60, s20
	s_addc_u32 s21, s61, s21
	s_and_b64 s[28:29], s[16:17], exec
	s_cselect_b32 s11, s21, s53
	s_cselect_b32 s13, s20, s52
	s_ashr_i32 s9, s8, 31
	s_lshl_b64 s[28:29], s[8:9], 19
	s_add_u32 s9, s33, s28
	v_readlane_b32 s28, v251, 25
	s_addc_u32 s28, s28, s29
	s_add_u32 s74, s9, 0xff800000
	s_addc_u32 s75, s28, -1
	s_and_b64 s[28:29], s[16:17], exec
	s_cselect_b32 s9, s75, s19
	s_cselect_b32 s96, s74, s18
	s_add_u32 s72, s52, 0x40080
	s_addc_u32 s73, s53, 0
	s_add_u32 s18, s18, 0x100
	v_mov_b32_e32 v34, 0
	s_addc_u32 s19, s19, 0
	s_mov_b32 s97, -2
	v_mov_b32_e32 v35, v34
	v_mov_b32_e32 v36, v34
	v_mov_b32_e32 v37, v34
	v_mov_b32_e32 v38, v34
	v_mov_b32_e32 v39, v34
	v_mov_b32_e32 v40, v34
	v_mov_b32_e32 v41, v34
	v_mov_b32_e32 v42, v34
	v_mov_b32_e32 v43, v34
	v_mov_b32_e32 v44, v34
	v_mov_b32_e32 v45, v34
	v_mov_b32_e32 v50, v34
	v_mov_b32_e32 v51, v34
	v_mov_b32_e32 v52, v34
	v_mov_b32_e32 v53, v34
	v_mov_b32_e32 v58, v34
	v_mov_b32_e32 v59, v34
	v_mov_b32_e32 v60, v34
	v_mov_b32_e32 v61, v34
	v_mov_b32_e32 v66, v34
	v_mov_b32_e32 v67, v34
	v_mov_b32_e32 v68, v34
	v_mov_b32_e32 v69, v34
	v_mov_b32_e32 v74, v34
	v_mov_b32_e32 v75, v34
	v_mov_b32_e32 v76, v34
	v_mov_b32_e32 v77, v34
	v_mov_b32_e32 v82, v34
	v_mov_b32_e32 v83, v34
	v_mov_b32_e32 v84, v34
	v_mov_b32_e32 v85, v34
	v_mov_b32_e32 v46, v34
	v_mov_b32_e32 v47, v34
	v_mov_b32_e32 v48, v34
	v_mov_b32_e32 v49, v34
	v_mov_b32_e32 v54, v34
	v_mov_b32_e32 v55, v34
	v_mov_b32_e32 v56, v34
	v_mov_b32_e32 v57, v34
	v_mov_b32_e32 v62, v34
	v_mov_b32_e32 v63, v34
	v_mov_b32_e32 v64, v34
	v_mov_b32_e32 v65, v34
	v_mov_b32_e32 v70, v34
	v_mov_b32_e32 v71, v34
	v_mov_b32_e32 v72, v34
	v_mov_b32_e32 v73, v34
	v_mov_b32_e32 v78, v34
	v_mov_b32_e32 v79, v34
	v_mov_b32_e32 v80, v34
	v_mov_b32_e32 v81, v34
	v_mov_b32_e32 v86, v34
	v_mov_b32_e32 v87, v34
	v_mov_b32_e32 v88, v34
	v_mov_b32_e32 v89, v34
	v_mov_b32_e32 v90, v34
	v_mov_b32_e32 v91, v34
	v_mov_b32_e32 v92, v34
	v_mov_b32_e32 v93, v34
	v_mov_b32_e32 v94, v34
	v_mov_b32_e32 v95, v34
	v_mov_b32_e32 v96, v34
	v_mov_b32_e32 v97, v34
	v_mov_b32_e32 v98, v34
	v_mov_b32_e32 v99, v34
	v_mov_b32_e32 v100, v34
	v_mov_b32_e32 v101, v34
	v_mov_b32_e32 v102, v34
	v_mov_b32_e32 v103, v34
	v_mov_b32_e32 v104, v34
	v_mov_b32_e32 v105, v34
	v_mov_b32_e32 v106, v34
	v_mov_b32_e32 v107, v34
	v_mov_b32_e32 v108, v34
	v_mov_b32_e32 v109, v34
	v_mov_b32_e32 v114, v34
	v_mov_b32_e32 v115, v34
	v_mov_b32_e32 v116, v34
	v_mov_b32_e32 v117, v34
	v_mov_b32_e32 v122, v34
	v_mov_b32_e32 v123, v34
	v_mov_b32_e32 v124, v34
	v_mov_b32_e32 v125, v34
	v_mov_b32_e32 v130, v34
	v_mov_b32_e32 v131, v34
	v_mov_b32_e32 v132, v34
	v_mov_b32_e32 v133, v34
	v_mov_b32_e32 v138, v34
	v_mov_b32_e32 v139, v34
	v_mov_b32_e32 v140, v34
	v_mov_b32_e32 v141, v34
	v_mov_b32_e32 v146, v34
	v_mov_b32_e32 v147, v34
	v_mov_b32_e32 v148, v34
	v_mov_b32_e32 v149, v34
	v_mov_b32_e32 v110, v34
	v_mov_b32_e32 v111, v34
	v_mov_b32_e32 v112, v34
	v_mov_b32_e32 v113, v34
	v_mov_b32_e32 v118, v34
	v_mov_b32_e32 v119, v34
	v_mov_b32_e32 v120, v34
	v_mov_b32_e32 v121, v34
	v_mov_b32_e32 v126, v34
	v_mov_b32_e32 v127, v34
	v_mov_b32_e32 v128, v34
	v_mov_b32_e32 v129, v34
	v_mov_b32_e32 v134, v34
	v_mov_b32_e32 v135, v34
	v_mov_b32_e32 v136, v34
	v_mov_b32_e32 v137, v34
	v_mov_b32_e32 v142, v34
	v_mov_b32_e32 v143, v34
	v_mov_b32_e32 v144, v34
	v_mov_b32_e32 v145, v34
	v_mov_b32_e32 v150, v34
	v_mov_b32_e32 v151, v34
	v_mov_b32_e32 v152, v34
	v_mov_b32_e32 v153, v34
	v_mov_b32_e32 v154, v34
	v_mov_b32_e32 v155, v34
	v_mov_b32_e32 v156, v34
	v_mov_b32_e32 v157, v34
	v_mov_b32_e32 v158, v34
	v_mov_b32_e32 v159, v34
	v_mov_b32_e32 v160, v34
	v_mov_b32_e32 v161, v34
	.p2align	6

; template <bool F8 = false, class Epi, class Sched>
; __device__ __forceinline__ void gemm_phase(LAS unsigned char* lds, const int lda, const int ldb, const int K, const Sched& S, const Epi& E) {
;     ...
; #pragma unroll
;         for (int a = 0; a < 2; ++a)
; #pragma unroll
;             for (int b = 0; b < 2; ++b)
; #pragma unroll
;                 for (int m = 0; m < 4; ++m)
; #pragma unroll
;                     for (int n = 0; n < 2; ++n) acc[a][b][m][n] = (f32x4){0.f, 0.f, 0.f, 0.f};
;         cur = nxt; cA = nA; cB = nB; ++ui;
.LBB0_435:
	s_add_u32 s11, s20, 0x100
	v_mov_b32_e32 v2, 0
	s_addc_u32 s28, s21, 0
	s_mov_b32 s29, -2
	v_mov_b32_e32 v3, v2
	v_mov_b32_e32 v4, v2
	v_mov_b32_e32 v5, v2
	v_mov_b32_e32 v6, v2
	v_mov_b32_e32 v7, v2
	v_mov_b32_e32 v8, v2
	v_mov_b32_e32 v9, v2
	v_mov_b32_e32 v10, v2
	v_mov_b32_e32 v11, v2
	v_mov_b32_e32 v12, v2
	v_mov_b32_e32 v13, v2
	v_mov_b32_e32 v18, v2
	v_mov_b32_e32 v19, v2
	v_mov_b32_e32 v20, v2
	v_mov_b32_e32 v21, v2
	v_mov_b32_e32 v26, v2
	v_mov_b32_e32 v27, v2
	v_mov_b32_e32 v28, v2
	v_mov_b32_e32 v29, v2
	v_mov_b32_e32 v34, v2
	v_mov_b32_e32 v35, v2
	v_mov_b32_e32 v36, v2
	v_mov_b32_e32 v37, v2
	v_mov_b32_e32 v42, v2
	v_mov_b32_e32 v43, v2
	v_mov_b32_e32 v44, v2
	v_mov_b32_e32 v45, v2
	v_mov_b32_e32 v50, v2
	v_mov_b32_e32 v51, v2
	v_mov_b32_e32 v52, v2
	v_mov_b32_e32 v53, v2
	v_mov_b32_e32 v14, v2
	v_mov_b32_e32 v15, v2
	v_mov_b32_e32 v16, v2
	v_mov_b32_e32 v17, v2
	v_mov_b32_e32 v22, v2
	v_mov_b32_e32 v23, v2
	v_mov_b32_e32 v24, v2
	v_mov_b32_e32 v25, v2
	v_mov_b32_e32 v30, v2
	v_mov_b32_e32 v31, v2
	v_mov_b32_e32 v32, v2
	v_mov_b32_e32 v33, v2
	v_mov_b32_e32 v38, v2
	v_mov_b32_e32 v39, v2
	v_mov_b32_e32 v40, v2
	v_mov_b32_e32 v41, v2
	v_mov_b32_e32 v46, v2
	v_mov_b32_e32 v47, v2
	v_mov_b32_e32 v48, v2
	v_mov_b32_e32 v49, v2
	v_mov_b32_e32 v54, v2
	v_mov_b32_e32 v55, v2
	v_mov_b32_e32 v56, v2
	v_mov_b32_e32 v57, v2
	v_mov_b32_e32 v58, v2
	v_mov_b32_e32 v59, v2
	v_mov_b32_e32 v60, v2
	v_mov_b32_e32 v61, v2
	v_mov_b32_e32 v62, v2
	v_mov_b32_e32 v63, v2
	v_mov_b32_e32 v64, v2
	v_mov_b32_e32 v65, v2
	v_mov_b32_e32 v66, v2
	v_mov_b32_e32 v67, v2
	v_mov_b32_e32 v68, v2
	v_mov_b32_e32 v69, v2
	v_mov_b32_e32 v70, v2
	v_mov_b32_e32 v71, v2
	v_mov_b32_e32 v72, v2
	v_mov_b32_e32 v73, v2
	v_mov_b32_e32 v74, v2
	v_mov_b32_e32 v75, v2
	v_mov_b32_e32 v76, v2
	v_mov_b32_e32 v77, v2
	v_mov_b32_e32 v82, v2
	v_mov_b32_e32 v83, v2
	v_mov_b32_e32 v84, v2
	v_mov_b32_e32 v85, v2
	v_mov_b32_e32 v90, v2
	v_mov_b32_e32 v91, v2
	v_mov_b32_e32 v92, v2
	v_mov_b32_e32 v93, v2
	v_mov_b32_e32 v98, v2
	v_mov_b32_e32 v99, v2
	v_mov_b32_e32 v100, v2
	v_mov_b32_e32 v101, v2
	v_mov_b32_e32 v106, v2
	v_mov_b32_e32 v107, v2
	v_mov_b32_e32 v108, v2
	v_mov_b32_e32 v109, v2
	v_mov_b32_e32 v114, v2
	v_mov_b32_e32 v115, v2
	v_mov_b32_e32 v116, v2
	v_mov_b32_e32 v117, v2
	v_mov_b32_e32 v78, v2
	v_mov_b32_e32 v79, v2
	v_mov_b32_e32 v80, v2
	v_mov_b32_e32 v81, v2
	v_mov_b32_e32 v86, v2
	v_mov_b32_e32 v87, v2
	v_mov_b32_e32 v88, v2
	v_mov_b32_e32 v89, v2
	v_mov_b32_e32 v94, v2
	v_mov_b32_e32 v95, v2
	v_mov_b32_e32 v96, v2
	v_mov_b32_e32 v97, v2
	v_mov_b32_e32 v102, v2
	v_mov_b32_e32 v103, v2
	v_mov_b32_e32 v104, v2
	v_mov_b32_e32 v105, v2
	v_mov_b32_e32 v110, v2
	v_mov_b32_e32 v111, v2
	v_mov_b32_e32 v112, v2
	v_mov_b32_e32 v113, v2
	v_mov_b32_e32 v118, v2
	v_mov_b32_e32 v119, v2
	v_mov_b32_e32 v120, v2
	v_mov_b32_e32 v121, v2
	v_mov_b32_e32 v122, v2
	v_mov_b32_e32 v123, v2
	v_mov_b32_e32 v124, v2
	v_mov_b32_e32 v125, v2
	v_mov_b32_e32 v126, v2
	v_mov_b32_e32 v127, v2
	v_mov_b32_e32 v128, v2
	v_mov_b32_e32 v129, v2
	.p2align	6

; template <bool F8 = false, class Epi, class Sched>
; __device__ __forceinline__ void gemm_phase(LAS unsigned char* lds, const int lda, const int ldb, const int K, const Sched& S, const Epi& E) {
;     ...
; #pragma unroll
;         for (int a = 0; a < 2; ++a)
; #pragma unroll
;             for (int b = 0; b < 2; ++b)
; #pragma unroll
;                 for (int m = 0; m < 4; ++m)
; #pragma unroll
;                     for (int n = 0; n < 2; ++n) acc[a][b][m][n] = (f32x4){0.f, 0.f, 0.f, 0.f};
;         cur = nxt; cA = nA; cB = nB; ++ui;
.LBB0_689:
	s_add_u32 s15, s52, 0x100
	v_mov_b32_e32 v2, 0
	s_addc_u32 s17, s53, 0
	s_mov_b32 s28, -2
	v_mov_b32_e32 v3, v2
	v_mov_b32_e32 v4, v2
	v_mov_b32_e32 v5, v2
	v_mov_b32_e32 v6, v2
	v_mov_b32_e32 v7, v2
	v_mov_b32_e32 v8, v2
	v_mov_b32_e32 v9, v2
	v_mov_b32_e32 v18, v2
	v_mov_b32_e32 v19, v2
	v_mov_b32_e32 v20, v2
	v_mov_b32_e32 v21, v2
	v_mov_b32_e32 v22, v2
	v_mov_b32_e32 v23, v2
	v_mov_b32_e32 v24, v2
	v_mov_b32_e32 v25, v2
	v_mov_b32_e32 v34, v2
	v_mov_b32_e32 v35, v2
	v_mov_b32_e32 v36, v2
	v_mov_b32_e32 v37, v2
	v_mov_b32_e32 v38, v2
	v_mov_b32_e32 v39, v2
	v_mov_b32_e32 v40, v2
	v_mov_b32_e32 v41, v2
	v_mov_b32_e32 v50, v2
	v_mov_b32_e32 v51, v2
	v_mov_b32_e32 v52, v2
	v_mov_b32_e32 v53, v2
	v_mov_b32_e32 v54, v2
	v_mov_b32_e32 v55, v2
	v_mov_b32_e32 v56, v2
	v_mov_b32_e32 v57, v2
	v_mov_b32_e32 v10, v2
	v_mov_b32_e32 v11, v2
	v_mov_b32_e32 v12, v2
	v_mov_b32_e32 v13, v2
	v_mov_b32_e32 v14, v2
	v_mov_b32_e32 v15, v2
	v_mov_b32_e32 v16, v2
	v_mov_b32_e32 v17, v2
	v_mov_b32_e32 v26, v2
	v_mov_b32_e32 v27, v2
	v_mov_b32_e32 v28, v2
	v_mov_b32_e32 v29, v2
	v_mov_b32_e32 v30, v2
	v_mov_b32_e32 v31, v2
	v_mov_b32_e32 v32, v2
	v_mov_b32_e32 v33, v2
	v_mov_b32_e32 v42, v2
	v_mov_b32_e32 v43, v2
	v_mov_b32_e32 v44, v2
	v_mov_b32_e32 v45, v2
	v_mov_b32_e32 v46, v2
	v_mov_b32_e32 v47, v2
	v_mov_b32_e32 v48, v2
	v_mov_b32_e32 v49, v2
	v_mov_b32_e32 v58, v2
	v_mov_b32_e32 v59, v2
	v_mov_b32_e32 v60, v2
	v_mov_b32_e32 v61, v2
	v_mov_b32_e32 v62, v2
	v_mov_b32_e32 v63, v2
	v_mov_b32_e32 v64, v2
	v_mov_b32_e32 v65, v2
	v_mov_b32_e32 v66, v2
	v_mov_b32_e32 v67, v2
	v_mov_b32_e32 v68, v2
	v_mov_b32_e32 v69, v2
	v_mov_b32_e32 v70, v2
	v_mov_b32_e32 v71, v2
	v_mov_b32_e32 v72, v2
	v_mov_b32_e32 v73, v2
	v_mov_b32_e32 v82, v2
	v_mov_b32_e32 v83, v2
	v_mov_b32_e32 v84, v2
	v_mov_b32_e32 v85, v2
	v_mov_b32_e32 v86, v2
	v_mov_b32_e32 v87, v2
	v_mov_b32_e32 v88, v2
	v_mov_b32_e32 v89, v2
	v_mov_b32_e32 v98, v2
	v_mov_b32_e32 v99, v2
	v_mov_b32_e32 v100, v2
	v_mov_b32_e32 v101, v2
	v_mov_b32_e32 v102, v2
	v_mov_b32_e32 v103, v2
	v_mov_b32_e32 v104, v2
	v_mov_b32_e32 v105, v2
	v_mov_b32_e32 v114, v2
	v_mov_b32_e32 v115, v2
	v_mov_b32_e32 v116, v2
	v_mov_b32_e32 v117, v2
	v_mov_b32_e32 v118, v2
	v_mov_b32_e32 v119, v2
	v_mov_b32_e32 v120, v2
	v_mov_b32_e32 v121, v2
	v_mov_b32_e32 v74, v2
	v_mov_b32_e32 v75, v2
	v_mov_b32_e32 v76, v2
	v_mov_b32_e32 v77, v2
	v_mov_b32_e32 v78, v2
	v_mov_b32_e32 v79, v2
	v_mov_b32_e32 v80, v2
	v_mov_b32_e32 v81, v2
	v_mov_b32_e32 v90, v2
	v_mov_b32_e32 v91, v2
	v_mov_b32_e32 v92, v2
	v_mov_b32_e32 v93, v2
	v_mov_b32_e32 v94, v2
	v_mov_b32_e32 v95, v2
	v_mov_b32_e32 v96, v2
	v_mov_b32_e32 v97, v2
	v_mov_b32_e32 v106, v2
	v_mov_b32_e32 v107, v2
	v_mov_b32_e32 v108, v2
	v_mov_b32_e32 v109, v2
	v_mov_b32_e32 v110, v2
	v_mov_b32_e32 v111, v2
	v_mov_b32_e32 v112, v2
	v_mov_b32_e32 v113, v2
	v_mov_b32_e32 v122, v2
	v_mov_b32_e32 v123, v2
	v_mov_b32_e32 v124, v2
	v_mov_b32_e32 v125, v2
	v_mov_b32_e32 v126, v2
	v_mov_b32_e32 v127, v2
	v_mov_b32_e32 v128, v2
	v_mov_b32_e32 v129, v2
	.p2align	6

;     __device__ __forceinline__ const char* ptrA(const Unit& u) const { return (u.sub ? A1 : A0) + (size_t)u.pm * aT; }
;     __device__ __forceinline__ const char* ptrB(const Unit& u) const { return (u.sub ? B1 : B0) + (size_t)u.pn * bT; }
;     __device__ __forceinline__ bool next(int i, Unit& u) const { const int L = i * G + c; if (L >= 256) return false; u.sub = L & 3; const int t = L >> 2; u.pm = 64 + (t >> 3); u.pn = t & 7; return true; }
; template <bool F8 = false, class Epi, class Sched>
; __device__ __forceinline__ void gemm_phase(LAS unsigned char* lds, const int lda, const int ldb, const int K, const Sched& S, const Epi& E) {
;     ...
;         const bool has_next = S.next(ui + 1, nxt);
;         const char* nA = has_next ? S.ptrA(nxt) : cA; const char* nB = has_next ? S.ptrB(nxt) : cB;
;     ...
; #pragma unroll
;         for (int a = 0; a < 2; ++a)
; #pragma unroll
;             for (int b = 0; b < 2; ++b)
; #pragma unroll
;                 for (int m = 0; m < 4; ++m)
; #pragma unroll
;                     for (int n = 0; n < 2; ++n) acc[a][b][m][n] = (f32x4){0.f, 0.f, 0.f, 0.f};
;         cur = nxt; cA = nA; cB = nB; ++ui;
.LBB0_806:
	s_ashr_i32 s11, s10, 31
	s_lshl_b64 s[14:15], s[10:11], 20
	s_add_u32 s14, s66, s14
	s_addc_u32 s15, s67, s15
	s_and_b64 s[16:17], s[12:13], exec
	s_cselect_b32 s11, s15, s19
	s_cselect_b32 s75, s14, s18
	s_ashr_i32 s9, s8, 31
	s_lshl_b64 s[16:17], s[8:9], 20
	v_readlane_b32 s9, v250, 13
	s_add_u32 s16, s9, s16
	v_readlane_b32 s9, v250, 14
	s_addc_u32 s17, s9, s17
	s_and_b64 s[28:29], s[12:13], exec
	s_cselect_b32 s9, s17, s21
	s_cselect_b32 s94, s16, s20
	s_add_u32 s18, s18, 0x80080
	s_addc_u32 s19, s19, 0
	s_add_u32 s95, s20, 0x100
	v_mov_b32_e32 v2, 0
	s_addc_u32 s96, s21, 0
	s_mov_b32 s28, -2
	v_mov_b32_e32 v3, v2
	v_mov_b32_e32 v4, v2
	v_mov_b32_e32 v5, v2
	v_mov_b32_e32 v6, v2
	v_mov_b32_e32 v7, v2
	v_mov_b32_e32 v8, v2
	v_mov_b32_e32 v9, v2
	v_mov_b32_e32 v10, v2
	v_mov_b32_e32 v11, v2
	v_mov_b32_e32 v12, v2
	v_mov_b32_e32 v13, v2
	v_mov_b32_e32 v18, v2
	v_mov_b32_e32 v19, v2
	v_mov_b32_e32 v20, v2
	v_mov_b32_e32 v21, v2
	v_mov_b32_e32 v26, v2
	v_mov_b32_e32 v27, v2
	v_mov_b32_e32 v28, v2
	v_mov_b32_e32 v29, v2
	v_mov_b32_e32 v34, v2
	v_mov_b32_e32 v35, v2
	v_mov_b32_e32 v36, v2
	v_mov_b32_e32 v37, v2
	v_mov_b32_e32 v42, v2
	v_mov_b32_e32 v43, v2
	v_mov_b32_e32 v44, v2
	v_mov_b32_e32 v45, v2
	v_mov_b32_e32 v50, v2
	v_mov_b32_e32 v51, v2
	v_mov_b32_e32 v52, v2
	v_mov_b32_e32 v53, v2
	v_mov_b32_e32 v14, v2
	v_mov_b32_e32 v15, v2
	v_mov_b32_e32 v16, v2
	v_mov_b32_e32 v17, v2
	v_mov_b32_e32 v22, v2
	v_mov_b32_e32 v23, v2
	v_mov_b32_e32 v24, v2
	v_mov_b32_e32 v25, v2
	v_mov_b32_e32 v30, v2
	v_mov_b32_e32 v31, v2
	v_mov_b32_e32 v32, v2
	v_mov_b32_e32 v33, v2
	v_mov_b32_e32 v38, v2
	v_mov_b32_e32 v39, v2
	v_mov_b32_e32 v40, v2
	v_mov_b32_e32 v41, v2
	v_mov_b32_e32 v46, v2
	v_mov_b32_e32 v47, v2
	v_mov_b32_e32 v48, v2
	v_mov_b32_e32 v49, v2
	v_mov_b32_e32 v54, v2
	v_mov_b32_e32 v55, v2
	v_mov_b32_e32 v56, v2
	v_mov_b32_e32 v57, v2
	v_mov_b32_e32 v58, v2
	v_mov_b32_e32 v59, v2
	v_mov_b32_e32 v60, v2
	v_mov_b32_e32 v61, v2
	v_mov_b32_e32 v62, v2
	v_mov_b32_e32 v63, v2
	v_mov_b32_e32 v64, v2
	v_mov_b32_e32 v65, v2
	v_mov_b32_e32 v66, v2
	v_mov_b32_e32 v67, v2
	v_mov_b32_e32 v68, v2
	v_mov_b32_e32 v69, v2
	v_mov_b32_e32 v70, v2
	v_mov_b32_e32 v71, v2
	v_mov_b32_e32 v72, v2
	v_mov_b32_e32 v73, v2
	v_mov_b32_e32 v74, v2
	v_mov_b32_e32 v75, v2
	v_mov_b32_e32 v76, v2
	v_mov_b32_e32 v77, v2
	v_mov_b32_e32 v82, v2
	v_mov_b32_e32 v83, v2
	v_mov_b32_e32 v84, v2
	v_mov_b32_e32 v85, v2
	v_mov_b32_e32 v90, v2
	v_mov_b32_e32 v91, v2
	v_mov_b32_e32 v92, v2
	v_mov_b32_e32 v93, v2
	v_mov_b32_e32 v98, v2
	v_mov_b32_e32 v99, v2
	v_mov_b32_e32 v100, v2
	v_mov_b32_e32 v101, v2
	v_mov_b32_e32 v106, v2
	v_mov_b32_e32 v107, v2
	v_mov_b32_e32 v108, v2
	v_mov_b32_e32 v109, v2
	v_mov_b32_e32 v114, v2
	v_mov_b32_e32 v115, v2
	v_mov_b32_e32 v116, v2
	v_mov_b32_e32 v117, v2
	v_mov_b32_e32 v78, v2
	v_mov_b32_e32 v79, v2
	v_mov_b32_e32 v80, v2
	v_mov_b32_e32 v81, v2
	v_mov_b32_e32 v86, v2
	v_mov_b32_e32 v87, v2
	v_mov_b32_e32 v88, v2
	v_mov_b32_e32 v89, v2
	v_mov_b32_e32 v94, v2
	v_mov_b32_e32 v95, v2
	v_mov_b32_e32 v96, v2
	v_mov_b32_e32 v97, v2
	v_mov_b32_e32 v102, v2
	v_mov_b32_e32 v103, v2
	v_mov_b32_e32 v104, v2
	v_mov_b32_e32 v105, v2
	v_mov_b32_e32 v110, v2
	v_mov_b32_e32 v111, v2
	v_mov_b32_e32 v112, v2
	v_mov_b32_e32 v113, v2
	v_mov_b32_e32 v118, v2
	v_mov_b32_e32 v119, v2
	v_mov_b32_e32 v120, v2
	v_mov_b32_e32 v121, v2
	v_mov_b32_e32 v122, v2
	v_mov_b32_e32 v123, v2
	v_mov_b32_e32 v124, v2
	v_mov_b32_e32 v125, v2
	v_mov_b32_e32 v126, v2
	v_mov_b32_e32 v127, v2
	v_mov_b32_e32 v128, v2
	v_mov_b32_e32 v129, v2
	.p2align	6

; template <bool F8 = false, class Epi, class Sched>
; __device__ __forceinline__ void gemm_phase(LAS unsigned char* lds, const int lda, const int ldb, const int K, const Sched& S, const Epi& E) {
;     ...
; #pragma unroll
;         for (int a = 0; a < 2; ++a)
; #pragma unroll
;             for (int b = 0; b < 2; ++b)
; #pragma unroll
;                 for (int m = 0; m < 4; ++m)
; #pragma unroll
;                     for (int n = 0; n < 2; ++n) acc[a][b][m][n] = (f32x4){0.f, 0.f, 0.f, 0.f};
;         cur = nxt; cA = nA; cB = nB; ++ui;
.LBB0_834:
	s_bfe_u32 s11, s14, 0x30002
	s_lshl_b32 s14, s11, 20
	v_readlane_b32 s20, v250, 13
	s_add_u32 s14, s20, s14
	v_readlane_b32 s20, v250, 14
	s_addc_u32 s20, s20, 0
	s_add_u32 s14, s14, s15
	s_addc_u32 s15, s20, s45
	s_and_b64 s[20:21], exec, s[8:9]
	s_cselect_b32 s75, s15, s19
	s_cselect_b32 s94, s14, s18
	s_add_u32 s16, s16, 0x80080
	s_addc_u32 s17, s17, 0
	s_add_u32 s95, s18, 0x100
	v_mov_b32_e32 v2, 0
	s_addc_u32 s96, s19, 0
	s_mov_b32 s28, -2
	v_mov_b32_e32 v3, v2
	v_mov_b32_e32 v4, v2
	v_mov_b32_e32 v5, v2
	v_mov_b32_e32 v6, v2
	v_mov_b32_e32 v7, v2
	v_mov_b32_e32 v8, v2
	v_mov_b32_e32 v9, v2
	v_mov_b32_e32 v14, v2
	v_mov_b32_e32 v15, v2
	v_mov_b32_e32 v16, v2
	v_mov_b32_e32 v17, v2
	v_mov_b32_e32 v18, v2
	v_mov_b32_e32 v19, v2
	v_mov_b32_e32 v20, v2
	v_mov_b32_e32 v21, v2
	v_mov_b32_e32 v30, v2
	v_mov_b32_e32 v31, v2
	v_mov_b32_e32 v32, v2
	v_mov_b32_e32 v33, v2
	v_mov_b32_e32 v34, v2
	v_mov_b32_e32 v35, v2
	v_mov_b32_e32 v36, v2
	v_mov_b32_e32 v37, v2
	v_mov_b32_e32 v46, v2
	v_mov_b32_e32 v47, v2
	v_mov_b32_e32 v48, v2
	v_mov_b32_e32 v49, v2
	v_mov_b32_e32 v50, v2
	v_mov_b32_e32 v51, v2
	v_mov_b32_e32 v52, v2
	v_mov_b32_e32 v53, v2
	v_mov_b32_e32 v10, v2
	v_mov_b32_e32 v11, v2
	v_mov_b32_e32 v12, v2
	v_mov_b32_e32 v13, v2
	v_mov_b32_e32 v22, v2
	v_mov_b32_e32 v23, v2
	v_mov_b32_e32 v24, v2
	v_mov_b32_e32 v25, v2
	v_mov_b32_e32 v26, v2
	v_mov_b32_e32 v27, v2
	v_mov_b32_e32 v28, v2
	v_mov_b32_e32 v29, v2
	v_mov_b32_e32 v38, v2
	v_mov_b32_e32 v39, v2
	v_mov_b32_e32 v40, v2
	v_mov_b32_e32 v41, v2
	v_mov_b32_e32 v42, v2
	v_mov_b32_e32 v43, v2
	v_mov_b32_e32 v44, v2
	v_mov_b32_e32 v45, v2
	v_mov_b32_e32 v54, v2
	v_mov_b32_e32 v55, v2
	v_mov_b32_e32 v56, v2
	v_mov_b32_e32 v57, v2
	v_mov_b32_e32 v58, v2
	v_mov_b32_e32 v59, v2
	v_mov_b32_e32 v60, v2
	v_mov_b32_e32 v61, v2
	v_mov_b32_e32 v62, v2
	v_mov_b32_e32 v63, v2
	v_mov_b32_e32 v64, v2
	v_mov_b32_e32 v65, v2
	v_mov_b32_e32 v66, v2
	v_mov_b32_e32 v67, v2
	v_mov_b32_e32 v68, v2
	v_mov_b32_e32 v69, v2
	v_mov_b32_e32 v70, v2
	v_mov_b32_e32 v71, v2
	v_mov_b32_e32 v72, v2
	v_mov_b32_e32 v73, v2
	v_mov_b32_e32 v74, v2
	v_mov_b32_e32 v75, v2
	v_mov_b32_e32 v76, v2
	v_mov_b32_e32 v77, v2
	v_mov_b32_e32 v82, v2
	v_mov_b32_e32 v83, v2
	v_mov_b32_e32 v84, v2
	v_mov_b32_e32 v85, v2
	v_mov_b32_e32 v90, v2
	v_mov_b32_e32 v91, v2
	v_mov_b32_e32 v92, v2
	v_mov_b32_e32 v93, v2
	v_mov_b32_e32 v98, v2
	v_mov_b32_e32 v99, v2
	v_mov_b32_e32 v100, v2
	v_mov_b32_e32 v101, v2
	v_mov_b32_e32 v106, v2
	v_mov_b32_e32 v107, v2
	v_mov_b32_e32 v108, v2
	v_mov_b32_e32 v109, v2
	v_mov_b32_e32 v114, v2
	v_mov_b32_e32 v115, v2
	v_mov_b32_e32 v116, v2
	v_mov_b32_e32 v117, v2
	v_mov_b32_e32 v78, v2
	v_mov_b32_e32 v79, v2
	v_mov_b32_e32 v80, v2
	v_mov_b32_e32 v81, v2
	v_mov_b32_e32 v86, v2
	v_mov_b32_e32 v87, v2
	v_mov_b32_e32 v88, v2
	v_mov_b32_e32 v89, v2
	v_mov_b32_e32 v94, v2
	v_mov_b32_e32 v95, v2
	v_mov_b32_e32 v96, v2
	v_mov_b32_e32 v97, v2
	v_mov_b32_e32 v102, v2
	v_mov_b32_e32 v103, v2
	v_mov_b32_e32 v104, v2
	v_mov_b32_e32 v105, v2
	v_mov_b32_e32 v110, v2
	v_mov_b32_e32 v111, v2
	v_mov_b32_e32 v112, v2
	v_mov_b32_e32 v113, v2
	v_mov_b32_e32 v118, v2
	v_mov_b32_e32 v119, v2
	v_mov_b32_e32 v120, v2
	v_mov_b32_e32 v121, v2
	v_mov_b32_e32 v122, v2
	v_mov_b32_e32 v123, v2
	v_mov_b32_e32 v124, v2
	v_mov_b32_e32 v125, v2
	v_mov_b32_e32 v126, v2
	v_mov_b32_e32 v127, v2
	v_mov_b32_e32 v128, v2
	v_mov_b32_e32 v129, v2
	.p2align	6

;     __device__ __forceinline__ const char* ptrA(const Unit& u) const { return (u.sub ? A1 : A0) + (size_t)u.pm * aT; }
;     __device__ __forceinline__ const char* ptrB(const Unit& u) const { return (u.sub ? B1 : B0) + (size_t)u.pn * bT; }
;     __device__ __forceinline__ bool next(int i, Unit& u) const { const int L = i * G + c; if (L >= 256) return false; u.sub = L & 3; const int t = L >> 2; u.pm = 64 + (t >> 3); u.pn = t & 7; return true; }
; template <bool F8 = false, class Epi, class Sched>
; __device__ __forceinline__ void gemm_phase(LAS unsigned char* lds, const int lda, const int ldb, const int K, const Sched& S, const Epi& E) {
;     ...
;         const bool has_next = S.next(ui + 1, nxt);
;         const char* nA = has_next ? S.ptrA(nxt) : cA; const char* nB = has_next ? S.ptrB(nxt) : cB;
;     ...
; #pragma unroll
;         for (int a = 0; a < 2; ++a)
; #pragma unroll
;             for (int b = 0; b < 2; ++b)
; #pragma unroll
;                 for (int m = 0; m < 4; ++m)
; #pragma unroll
;                     for (int n = 0; n < 2; ++n) acc[a][b][m][n] = (f32x4){0.f, 0.f, 0.f, 0.f};
;         cur = nxt; cA = nA; cB = nB; ++ui;
.LBB0_1061:
	s_ashr_i32 s73, s72, 31
	s_lshl_b64 s[16:17], s[72:73], 20
	s_add_u32 s16, s82, s16
	s_addc_u32 s17, s83, s17
	s_and_b64 s[20:21], s[14:15], exec
	s_cselect_b32 s13, s17, s53
	s_cselect_b32 s26, s16, s52
	s_ashr_i32 s9, s8, 31
	s_lshl_b64 s[20:21], s[8:9], 20
	s_add_u32 s20, s86, s20
	s_addc_u32 s21, s87, s21
	s_and_b64 s[28:29], s[14:15], exec
	s_cselect_b32 s9, s21, s75
	s_cselect_b32 s27, s20, s74
	s_add_u32 vcc_lo, s52, 0x80080
	s_addc_u32 vcc_hi, s53, 0
	s_add_u32 s73, s74, 0x100
	v_mov_b32_e32 v2, 0
	s_addc_u32 s28, s75, 0
	s_mov_b32 s29, -2
	v_mov_b32_e32 v3, v2
	v_mov_b32_e32 v4, v2
	v_mov_b32_e32 v5, v2
	v_mov_b32_e32 v6, v2
	v_mov_b32_e32 v7, v2
	v_mov_b32_e32 v8, v2
	v_mov_b32_e32 v9, v2
	v_mov_b32_e32 v18, v2
	v_mov_b32_e32 v19, v2
	v_mov_b32_e32 v20, v2
	v_mov_b32_e32 v21, v2
	v_mov_b32_e32 v22, v2
	v_mov_b32_e32 v23, v2
	v_mov_b32_e32 v24, v2
	v_mov_b32_e32 v25, v2
	v_mov_b32_e32 v34, v2
	v_mov_b32_e32 v35, v2
	v_mov_b32_e32 v36, v2
	v_mov_b32_e32 v37, v2
	v_mov_b32_e32 v38, v2
	v_mov_b32_e32 v39, v2
	v_mov_b32_e32 v40, v2
	v_mov_b32_e32 v41, v2
	v_mov_b32_e32 v50, v2
	v_mov_b32_e32 v51, v2
	v_mov_b32_e32 v52, v2
	v_mov_b32_e32 v53, v2
	v_mov_b32_e32 v54, v2
	v_mov_b32_e32 v55, v2
	v_mov_b32_e32 v56, v2
	v_mov_b32_e32 v57, v2
	v_mov_b32_e32 v10, v2
	v_mov_b32_e32 v11, v2
	v_mov_b32_e32 v12, v2
	v_mov_b32_e32 v13, v2
	v_mov_b32_e32 v14, v2
	v_mov_b32_e32 v15, v2
	v_mov_b32_e32 v16, v2
	v_mov_b32_e32 v17, v2
	v_mov_b32_e32 v26, v2
	v_mov_b32_e32 v27, v2
	v_mov_b32_e32 v28, v2
	v_mov_b32_e32 v29, v2
	v_mov_b32_e32 v30, v2
	v_mov_b32_e32 v31, v2
	v_mov_b32_e32 v32, v2
	v_mov_b32_e32 v33, v2
	v_mov_b32_e32 v42, v2
	v_mov_b32_e32 v43, v2
	v_mov_b32_e32 v44, v2
	v_mov_b32_e32 v45, v2
	v_mov_b32_e32 v46, v2
	v_mov_b32_e32 v47, v2
	v_mov_b32_e32 v48, v2
	v_mov_b32_e32 v49, v2
	v_mov_b32_e32 v58, v2
	v_mov_b32_e32 v59, v2
	v_mov_b32_e32 v60, v2
	v_mov_b32_e32 v61, v2
	v_mov_b32_e32 v62, v2
	v_mov_b32_e32 v63, v2
	v_mov_b32_e32 v64, v2
	v_mov_b32_e32 v65, v2
	v_mov_b32_e32 v66, v2
	v_mov_b32_e32 v67, v2
	v_mov_b32_e32 v68, v2
	v_mov_b32_e32 v69, v2
	v_mov_b32_e32 v70, v2
	v_mov_b32_e32 v71, v2
	v_mov_b32_e32 v72, v2
	v_mov_b32_e32 v73, v2
	v_mov_b32_e32 v82, v2
	v_mov_b32_e32 v83, v2
	v_mov_b32_e32 v84, v2
	v_mov_b32_e32 v85, v2
	v_mov_b32_e32 v86, v2
	v_mov_b32_e32 v87, v2
	v_mov_b32_e32 v88, v2
	v_mov_b32_e32 v89, v2
	v_mov_b32_e32 v98, v2
	v_mov_b32_e32 v99, v2
	v_mov_b32_e32 v100, v2
	v_mov_b32_e32 v101, v2
	v_mov_b32_e32 v102, v2
	v_mov_b32_e32 v103, v2
	v_mov_b32_e32 v104, v2
	v_mov_b32_e32 v105, v2
	v_mov_b32_e32 v114, v2
	v_mov_b32_e32 v115, v2
	v_mov_b32_e32 v116, v2
	v_mov_b32_e32 v117, v2
	v_mov_b32_e32 v118, v2
	v_mov_b32_e32 v119, v2
	v_mov_b32_e32 v120, v2
	v_mov_b32_e32 v121, v2
	v_mov_b32_e32 v74, v2
	v_mov_b32_e32 v75, v2
	v_mov_b32_e32 v76, v2
	v_mov_b32_e32 v77, v2
	v_mov_b32_e32 v78, v2
	v_mov_b32_e32 v79, v2
	v_mov_b32_e32 v80, v2
	v_mov_b32_e32 v81, v2
	v_mov_b32_e32 v90, v2
	v_mov_b32_e32 v91, v2
	v_mov_b32_e32 v92, v2
	v_mov_b32_e32 v93, v2
	v_mov_b32_e32 v94, v2
	v_mov_b32_e32 v95, v2
	v_mov_b32_e32 v96, v2
	v_mov_b32_e32 v97, v2
	v_mov_b32_e32 v106, v2
	v_mov_b32_e32 v107, v2
	v_mov_b32_e32 v108, v2
	v_mov_b32_e32 v109, v2
	v_mov_b32_e32 v110, v2
	v_mov_b32_e32 v111, v2
	v_mov_b32_e32 v112, v2
	v_mov_b32_e32 v113, v2
	v_mov_b32_e32 v122, v2
	v_mov_b32_e32 v123, v2
	v_mov_b32_e32 v124, v2
	v_mov_b32_e32 v125, v2
	v_mov_b32_e32 v126, v2
	v_mov_b32_e32 v127, v2
	v_mov_b32_e32 v128, v2
	v_mov_b32_e32 v129, v2
	.p2align	6

; template <bool F8 = false, class Epi, class Sched>
; __device__ __forceinline__ void gemm_phase(LAS unsigned char* lds, const int lda, const int ldb, const int K, const Sched& S, const Epi& E) {
;     ...
; #pragma unroll
;         for (int a = 0; a < 2; ++a)
; #pragma unroll
;             for (int b = 0; b < 2; ++b)
; #pragma unroll
;                 for (int m = 0; m < 4; ++m)
; #pragma unroll
;                     for (int n = 0; n < 2; ++n) acc[a][b][m][n] = (f32x4){0.f, 0.f, 0.f, 0.f};
;         cur = nxt; cA = nA; cB = nB; ++ui;
.LBB0_1148:
	s_add_u32 s28, s18, 0x100
	v_mov_b32_e32 v2, 0
	s_addc_u32 s29, s19, 0
	s_mov_b32 s94, -2
	v_mov_b32_e32 v3, v2
	v_mov_b32_e32 v4, v2
	v_mov_b32_e32 v5, v2
	v_mov_b32_e32 v6, v2
	v_mov_b32_e32 v7, v2
	v_mov_b32_e32 v8, v2
	v_mov_b32_e32 v9, v2
	v_mov_b32_e32 v10, v2
	v_mov_b32_e32 v11, v2
	v_mov_b32_e32 v12, v2
	v_mov_b32_e32 v13, v2
	v_mov_b32_e32 v18, v2
	v_mov_b32_e32 v19, v2
	v_mov_b32_e32 v20, v2
	v_mov_b32_e32 v21, v2
	v_mov_b32_e32 v26, v2
	v_mov_b32_e32 v27, v2
	v_mov_b32_e32 v28, v2
	v_mov_b32_e32 v29, v2
	v_mov_b32_e32 v34, v2
	v_mov_b32_e32 v35, v2
	v_mov_b32_e32 v36, v2
	v_mov_b32_e32 v37, v2
	v_mov_b32_e32 v42, v2
	v_mov_b32_e32 v43, v2
	v_mov_b32_e32 v44, v2
	v_mov_b32_e32 v45, v2
	v_mov_b32_e32 v50, v2
	v_mov_b32_e32 v51, v2
	v_mov_b32_e32 v52, v2
	v_mov_b32_e32 v53, v2
	v_mov_b32_e32 v14, v2
	v_mov_b32_e32 v15, v2
	v_mov_b32_e32 v16, v2
	v_mov_b32_e32 v17, v2
	v_mov_b32_e32 v22, v2
	v_mov_b32_e32 v23, v2
	v_mov_b32_e32 v24, v2
	v_mov_b32_e32 v25, v2
	v_mov_b32_e32 v30, v2
	v_mov_b32_e32 v31, v2
	v_mov_b32_e32 v32, v2
	v_mov_b32_e32 v33, v2
	v_mov_b32_e32 v38, v2
	v_mov_b32_e32 v39, v2
	v_mov_b32_e32 v40, v2
	v_mov_b32_e32 v41, v2
	v_mov_b32_e32 v46, v2
	v_mov_b32_e32 v47, v2
	v_mov_b32_e32 v48, v2
	v_mov_b32_e32 v49, v2
	v_mov_b32_e32 v54, v2
	v_mov_b32_e32 v55, v2
	v_mov_b32_e32 v56, v2
	v_mov_b32_e32 v57, v2
	v_mov_b32_e32 v58, v2
	v_mov_b32_e32 v59, v2
	v_mov_b32_e32 v60, v2
	v_mov_b32_e32 v61, v2
	v_mov_b32_e32 v62, v2
	v_mov_b32_e32 v63, v2
	v_mov_b32_e32 v64, v2
	v_mov_b32_e32 v65, v2
	v_mov_b32_e32 v66, v2
	v_mov_b32_e32 v67, v2
	v_mov_b32_e32 v68, v2
	v_mov_b32_e32 v69, v2
	v_mov_b32_e32 v70, v2
	v_mov_b32_e32 v71, v2
	v_mov_b32_e32 v72, v2
	v_mov_b32_e32 v73, v2
	v_mov_b32_e32 v74, v2
	v_mov_b32_e32 v75, v2
	v_mov_b32_e32 v76, v2
	v_mov_b32_e32 v77, v2
	v_mov_b32_e32 v82, v2
	v_mov_b32_e32 v83, v2
	v_mov_b32_e32 v84, v2
	v_mov_b32_e32 v85, v2
	v_mov_b32_e32 v90, v2
	v_mov_b32_e32 v91, v2
	v_mov_b32_e32 v92, v2
	v_mov_b32_e32 v93, v2
	v_mov_b32_e32 v98, v2
	v_mov_b32_e32 v99, v2
	v_mov_b32_e32 v100, v2
	v_mov_b32_e32 v101, v2
	v_mov_b32_e32 v106, v2
	v_mov_b32_e32 v107, v2
	v_mov_b32_e32 v108, v2
	v_mov_b32_e32 v109, v2
	v_mov_b32_e32 v114, v2
	v_mov_b32_e32 v115, v2
	v_mov_b32_e32 v116, v2
	v_mov_b32_e32 v117, v2
	v_mov_b32_e32 v78, v2
	v_mov_b32_e32 v79, v2
	v_mov_b32_e32 v80, v2
	v_mov_b32_e32 v81, v2
	v_mov_b32_e32 v86, v2
	v_mov_b32_e32 v87, v2
	v_mov_b32_e32 v88, v2
	v_mov_b32_e32 v89, v2
	v_mov_b32_e32 v94, v2
	v_mov_b32_e32 v95, v2
	v_mov_b32_e32 v96, v2
	v_mov_b32_e32 v97, v2
	v_mov_b32_e32 v102, v2
	v_mov_b32_e32 v103, v2
	v_mov_b32_e32 v104, v2
	v_mov_b32_e32 v105, v2
	v_mov_b32_e32 v110, v2
	v_mov_b32_e32 v111, v2
	v_mov_b32_e32 v112, v2
	v_mov_b32_e32 v113, v2
	v_mov_b32_e32 v118, v2
	v_mov_b32_e32 v119, v2
	v_mov_b32_e32 v120, v2
	v_mov_b32_e32 v121, v2
	v_mov_b32_e32 v122, v2
	v_mov_b32_e32 v123, v2
	v_mov_b32_e32 v124, v2
	v_mov_b32_e32 v125, v2
	v_mov_b32_e32 v126, v2
	v_mov_b32_e32 v127, v2
	v_mov_b32_e32 v128, v2
	v_mov_b32_e32 v129, v2
	.p2align	6

; template <bool F8 = false, class Epi, class Sched>
; __device__ __forceinline__ void gemm_phase(LAS unsigned char* lds, const int lda, const int ldb, const int K, const Sched& S, const Epi& E) {
;     ...
; #pragma unroll
;         for (int a = 0; a < 2; ++a)
; #pragma unroll
;             for (int b = 0; b < 2; ++b)
; #pragma unroll
;                 for (int m = 0; m < 4; ++m)
; #pragma unroll
;                     for (int n = 0; n < 2; ++n) acc[a][b][m][n] = (f32x4){0.f, 0.f, 0.f, 0.f};
;         cur = nxt; cA = nA; cB = nB; ++ui;
.LBB0_1176:
	s_add_u32 s28, s18, 0x100
	v_mov_b32_e32 v2, 0
	s_addc_u32 s29, s19, 0
	s_mov_b32 s96, -2
	v_mov_b32_e32 v3, v2
	v_mov_b32_e32 v4, v2
	v_mov_b32_e32 v5, v2
	v_mov_b32_e32 v6, v2
	v_mov_b32_e32 v7, v2
	v_mov_b32_e32 v8, v2
	v_mov_b32_e32 v9, v2
	v_mov_b32_e32 v14, v2
	v_mov_b32_e32 v15, v2
	v_mov_b32_e32 v16, v2
	v_mov_b32_e32 v17, v2
	v_mov_b32_e32 v18, v2
	v_mov_b32_e32 v19, v2
	v_mov_b32_e32 v20, v2
	v_mov_b32_e32 v21, v2
	v_mov_b32_e32 v30, v2
	v_mov_b32_e32 v31, v2
	v_mov_b32_e32 v32, v2
	v_mov_b32_e32 v33, v2
	v_mov_b32_e32 v34, v2
	v_mov_b32_e32 v35, v2
	v_mov_b32_e32 v36, v2
	v_mov_b32_e32 v37, v2
	v_mov_b32_e32 v46, v2
	v_mov_b32_e32 v47, v2
	v_mov_b32_e32 v48, v2
	v_mov_b32_e32 v49, v2
	v_mov_b32_e32 v50, v2
	v_mov_b32_e32 v51, v2
	v_mov_b32_e32 v52, v2
	v_mov_b32_e32 v53, v2
	v_mov_b32_e32 v10, v2
	v_mov_b32_e32 v11, v2
	v_mov_b32_e32 v12, v2
	v_mov_b32_e32 v13, v2
	v_mov_b32_e32 v22, v2
	v_mov_b32_e32 v23, v2
	v_mov_b32_e32 v24, v2
	v_mov_b32_e32 v25, v2
	v_mov_b32_e32 v26, v2
	v_mov_b32_e32 v27, v2
	v_mov_b32_e32 v28, v2
	v_mov_b32_e32 v29, v2
	v_mov_b32_e32 v38, v2
	v_mov_b32_e32 v39, v2
	v_mov_b32_e32 v40, v2
	v_mov_b32_e32 v41, v2
	v_mov_b32_e32 v42, v2
	v_mov_b32_e32 v43, v2
	v_mov_b32_e32 v44, v2
	v_mov_b32_e32 v45, v2
	v_mov_b32_e32 v54, v2
	v_mov_b32_e32 v55, v2
	v_mov_b32_e32 v56, v2
	v_mov_b32_e32 v57, v2
	v_mov_b32_e32 v58, v2
	v_mov_b32_e32 v59, v2
	v_mov_b32_e32 v60, v2
	v_mov_b32_e32 v61, v2
	v_mov_b32_e32 v62, v2
	v_mov_b32_e32 v63, v2
	v_mov_b32_e32 v64, v2
	v_mov_b32_e32 v65, v2
	v_mov_b32_e32 v66, v2
	v_mov_b32_e32 v67, v2
	v_mov_b32_e32 v68, v2
	v_mov_b32_e32 v69, v2
	v_mov_b32_e32 v70, v2
	v_mov_b32_e32 v71, v2
	v_mov_b32_e32 v72, v2
	v_mov_b32_e32 v73, v2
	v_mov_b32_e32 v74, v2
	v_mov_b32_e32 v75, v2
	v_mov_b32_e32 v76, v2
	v_mov_b32_e32 v77, v2
	v_mov_b32_e32 v82, v2
	v_mov_b32_e32 v83, v2
	v_mov_b32_e32 v84, v2
	v_mov_b32_e32 v85, v2
	v_mov_b32_e32 v90, v2
	v_mov_b32_e32 v91, v2
	v_mov_b32_e32 v92, v2
	v_mov_b32_e32 v93, v2
	v_mov_b32_e32 v98, v2
	v_mov_b32_e32 v99, v2
	v_mov_b32_e32 v100, v2
	v_mov_b32_e32 v101, v2
	v_mov_b32_e32 v106, v2
	v_mov_b32_e32 v107, v2
	v_mov_b32_e32 v108, v2
	v_mov_b32_e32 v109, v2
	v_mov_b32_e32 v114, v2
	v_mov_b32_e32 v115, v2
	v_mov_b32_e32 v116, v2
	v_mov_b32_e32 v117, v2
	v_mov_b32_e32 v78, v2
	v_mov_b32_e32 v79, v2
	v_mov_b32_e32 v80, v2
	v_mov_b32_e32 v81, v2
	v_mov_b32_e32 v86, v2
	v_mov_b32_e32 v87, v2
	v_mov_b32_e32 v88, v2
	v_mov_b32_e32 v89, v2
	v_mov_b32_e32 v94, v2
	v_mov_b32_e32 v95, v2
	v_mov_b32_e32 v96, v2
	v_mov_b32_e32 v97, v2
	v_mov_b32_e32 v102, v2
	v_mov_b32_e32 v103, v2
	v_mov_b32_e32 v104, v2
	v_mov_b32_e32 v105, v2
	v_mov_b32_e32 v110, v2
	v_mov_b32_e32 v111, v2
	v_mov_b32_e32 v112, v2
	v_mov_b32_e32 v113, v2
	v_mov_b32_e32 v118, v2
	v_mov_b32_e32 v119, v2
	v_mov_b32_e32 v120, v2
	v_mov_b32_e32 v121, v2
	v_mov_b32_e32 v122, v2
	v_mov_b32_e32 v123, v2
	v_mov_b32_e32 v124, v2
	v_mov_b32_e32 v125, v2
	v_mov_b32_e32 v126, v2
	v_mov_b32_e32 v127, v2
	v_mov_b32_e32 v128, v2
	v_mov_b32_e32 v129, v2
	.p2align	6
